# prep x->bf16 loop: 4 chunk loads issued together with counted vmcnt; phase_final: gain loads hoisted, next-token loads issued before current stores
# speedup vs baseline: 1.0355x; 1.0023x over previous
; DI unsigned pack2(float a, float b) { return (unsigned)f2bf(a) | ((unsigned)f2bf(b) << 16); }
; DI float wave_sum(float v) { for (int o = 32; o > 0; o >>= 1) v += __shfl_xor(v, o); return v; }
; DI void phase_prep(const Params& p) {
;     ...
;   for (int it = blockIdx.x; it < T / 8; it += gridDim.x) {
;     int tok = it * 8 + wid; const float* xr = xrow(p, tok); float ss = 0;
;     for (int i = 0; i < 4; ++i) { f32x4 v = *(const f32x4*)(xr + i * 256 + lane * 4); ss += v[0] * v[0] + v[1] * v[1] + v[2] * v[2] + v[3] * v[3];
;       u32x2 w = {pack2(v[0], v[1]), pack2(v[2], v[3])}; *(u32x2*)(xb + (size_t)tok * LDP + i * 256 + lane * 4) = w; }
;     ss = wave_sum(ss); if (lane == 0) r0[tok] = rsqrtf(ss * (1.f / 1024) + EPS);
;   }
.LBB0_58:
	v_add_u32_e32 v24, 0xffffc000, v12
	v_ashrrev_i32_e32 v13, 31, v12
	v_cmp_gt_i32_e64 s[6:7], s4, v12
	s_waitcnt lgkmcnt(0)
	s_nop 0
	v_cndmask_b32_e64 v25, 0, v13, s[6:7]
	v_cndmask_b32_e64 v24, v24, v12, s[6:7]
	v_cndmask_b32_e64 v27, v18, v19, s[6:7]
	v_cndmask_b32_e64 v26, v20, v21, s[6:7]
	v_lshlrev_b64 v[24:25], 12, v[24:25]
	v_lshl_add_u64 v[24:25], v[26:27], 0, v[24:25]
	v_lshl_add_u64 v[36:37], v[24:25], 0, v[10:11]
	global_load_dwordx4 v[24:27], v[36:37], off
	global_load_dwordx4 v[220:223], v[36:37], off offset:1024
	global_load_dwordx4 v[224:227], v[36:37], off offset:2048
	global_load_dwordx4 v[228:231], v[36:37], off offset:3072
	v_mad_i64_i32 v[40:41], s[6:7], v12, s5, v[6:7]
	s_waitcnt vmcnt(3)
	v_and_b32_sdwa v29, v24, v23 dst_sel:DWORD dst_unused:UNUSED_PAD src0_sel:WORD_1 src1_sel:DWORD
	v_and_b32_sdwa v30, v27, v23 dst_sel:DWORD dst_unused:UNUSED_PAD src0_sel:WORD_1 src1_sel:DWORD
	v_and_b32_sdwa v31, v25, v23 dst_sel:DWORD dst_unused:UNUSED_PAD src0_sel:WORD_1 src1_sel:DWORD
	v_and_b32_sdwa v28, v26, v23 dst_sel:DWORD dst_unused:UNUSED_PAD src0_sel:WORD_1 src1_sel:DWORD
	v_add3_u32 v32, v24, v29, s10
	v_add3_u32 v29, v27, v30, s10
	v_add3_u32 v30, v25, v31, s10
	v_add3_u32 v28, v26, v28, s10
	v_and_b32_e32 v29, 0xffff0000, v29
	v_and_b32_e32 v30, 0xffff0000, v30
	v_or_b32_sdwa v29, v29, v28 dst_sel:DWORD dst_unused:UNUSED_PAD src0_sel:DWORD src1_sel:WORD_1
	v_or_b32_sdwa v28, v30, v32 dst_sel:DWORD dst_unused:UNUSED_PAD src0_sel:DWORD src1_sel:WORD_1
	global_store_dwordx2 v[40:41], v[28:29], off
	v_mul_f32_e32 v25, v25, v25
	v_fmac_f32_e32 v25, v24, v24
	v_fmac_f32_e32 v25, v26, v26
	v_fmac_f32_e32 v25, v27, v27
	s_waitcnt vmcnt(3)
	v_and_b32_sdwa v33, v220, v23 dst_sel:DWORD dst_unused:UNUSED_PAD src0_sel:WORD_1 src1_sel:DWORD
	v_and_b32_sdwa v34, v223, v23 dst_sel:DWORD dst_unused:UNUSED_PAD src0_sel:WORD_1 src1_sel:DWORD
	v_and_b32_sdwa v35, v221, v23 dst_sel:DWORD dst_unused:UNUSED_PAD src0_sel:WORD_1 src1_sel:DWORD
	v_and_b32_sdwa v32, v222, v23 dst_sel:DWORD dst_unused:UNUSED_PAD src0_sel:WORD_1 src1_sel:DWORD
	v_add3_u32 v38, v220, v33, s10
	v_add3_u32 v33, v223, v34, s10
	v_add3_u32 v34, v221, v35, s10
	v_add3_u32 v32, v222, v32, s10
	v_and_b32_e32 v33, 0xffff0000, v33
	v_and_b32_e32 v34, 0xffff0000, v34
	v_or_b32_sdwa v33, v33, v32 dst_sel:DWORD dst_unused:UNUSED_PAD src0_sel:DWORD src1_sel:WORD_1
	v_or_b32_sdwa v32, v34, v38 dst_sel:DWORD dst_unused:UNUSED_PAD src0_sel:DWORD src1_sel:WORD_1
	global_store_dwordx2 v[40:41], v[32:33], off offset:512
	v_mul_f32_e32 v24, v221, v221
	v_fmac_f32_e32 v24, v220, v220
	v_fmac_f32_e32 v24, v222, v222
	v_fmac_f32_e32 v24, v223, v223
	v_add_f32_e32 v24, v25, v24
	s_waitcnt vmcnt(3)
	v_and_b32_sdwa v39, v224, v23 dst_sel:DWORD dst_unused:UNUSED_PAD src0_sel:WORD_1 src1_sel:DWORD
	v_and_b32_sdwa v42, v227, v23 dst_sel:DWORD dst_unused:UNUSED_PAD src0_sel:WORD_1 src1_sel:DWORD
	v_and_b32_sdwa v43, v225, v23 dst_sel:DWORD dst_unused:UNUSED_PAD src0_sel:WORD_1 src1_sel:DWORD
	v_and_b32_sdwa v38, v226, v23 dst_sel:DWORD dst_unused:UNUSED_PAD src0_sel:WORD_1 src1_sel:DWORD
	v_add3_u32 v44, v224, v39, s10
	v_add3_u32 v39, v227, v42, s10
	v_add3_u32 v42, v225, v43, s10
	v_add3_u32 v38, v226, v38, s10
	v_and_b32_e32 v39, 0xffff0000, v39
	v_and_b32_e32 v42, 0xffff0000, v42
	v_or_b32_sdwa v39, v39, v38 dst_sel:DWORD dst_unused:UNUSED_PAD src0_sel:DWORD src1_sel:WORD_1
	v_or_b32_sdwa v38, v42, v44 dst_sel:DWORD dst_unused:UNUSED_PAD src0_sel:DWORD src1_sel:WORD_1
	global_store_dwordx2 v[40:41], v[38:39], off offset:1024
	v_mul_f32_e32 v25, v225, v225
	v_fmac_f32_e32 v25, v224, v224
	v_fmac_f32_e32 v25, v226, v226
	v_fmac_f32_e32 v25, v227, v227
	v_add_f32_e32 v24, v24, v25
	s_waitcnt vmcnt(3)
	v_mul_f32_e32 v25, v229, v229
	v_fmac_f32_e32 v25, v228, v228
	v_fmac_f32_e32 v25, v230, v230
	v_fmac_f32_e32 v25, v231, v231
	v_add_f32_e32 v24, v24, v25
	ds_bpermute_b32 v25, v3, v24
	v_and_b32_sdwa v27, v228, v23 dst_sel:DWORD dst_unused:UNUSED_PAD src0_sel:WORD_1 src1_sel:DWORD
	v_add3_u32 v28, v228, v27, s10
	v_and_b32_sdwa v27, v231, v23 dst_sel:DWORD dst_unused:UNUSED_PAD src0_sel:WORD_1 src1_sel:DWORD
	v_and_b32_sdwa v29, v229, v23 dst_sel:DWORD dst_unused:UNUSED_PAD src0_sel:WORD_1 src1_sel:DWORD
	s_waitcnt lgkmcnt(0)
	v_add_f32_e32 v24, v24, v25
	ds_bpermute_b32 v25, v5, v24
	v_and_b32_sdwa v26, v230, v23 dst_sel:DWORD dst_unused:UNUSED_PAD src0_sel:WORD_1 src1_sel:DWORD
	v_add3_u32 v27, v231, v27, s10
	v_add3_u32 v29, v229, v29, s10
	v_add3_u32 v26, v230, v26, s10
	s_waitcnt lgkmcnt(0)
	v_add_f32_e32 v24, v24, v25
	ds_bpermute_b32 v25, v14, v24
	v_and_b32_e32 v27, 0xffff0000, v27
	v_and_b32_e32 v29, 0xffff0000, v29
	v_or_b32_sdwa v27, v27, v26 dst_sel:DWORD dst_unused:UNUSED_PAD src0_sel:DWORD src1_sel:WORD_1
	v_or_b32_sdwa v26, v29, v28 dst_sel:DWORD dst_unused:UNUSED_PAD src0_sel:DWORD src1_sel:WORD_1
	s_waitcnt lgkmcnt(0)
	v_add_f32_e32 v24, v24, v25
	ds_bpermute_b32 v25, v15, v24
	global_store_dwordx2 v[40:41], v[26:27], off offset:1536
	s_waitcnt lgkmcnt(0)
	v_add_f32_e32 v24, v24, v25
	ds_bpermute_b32 v25, v16, v24
	s_waitcnt lgkmcnt(0)
	v_add_f32_e32 v24, v24, v25
	ds_bpermute_b32 v25, v17, v24
	s_and_saveexec_b64 s[8:9], vcc
	s_cbranch_execz .LBB0_57
	s_waitcnt lgkmcnt(0)
	v_add_f32_e32 v24, v24, v25
	v_fmamk_f32 v24, v24, 0x3a800000, v22
	v_mul_f32_e32 v25, 0x4b800000, v24
	v_cmp_gt_f32_e64 s[6:7], s11, v24
	s_nop 1
	v_cndmask_b32_e64 v24, v24, v25, s[6:7]
	v_rsq_f32_e32 v24, v24
	s_nop 0
	v_mul_f32_e32 v25, 0x45800000, v24
	v_cndmask_b32_e64 v26, v24, v25, s[6:7]
	v_lshl_add_u64 v[24:25], v[12:13], 2, v[8:9]
	global_store_dword v[24:25], v26, off
	s_branch .LBB0_57

; DI void phase_final(const Params& p) {
;     ...
;   for (int it = blockIdx.x; it < T / 8; it += gridDim.x) {
;     int tok = it * 8 + wid; float rs = rsqrtf(ssq[tok] * (1.f / 1024) + EPS); float* hr = p.out + (size_t)tok * 1024;
;     for (int i = 0; i < 4; ++i) { f32x4 v = *(f32x4*)(hr + i * 256 + lane * 4); f32x4 g = *(const f32x4*)(p.final_g + i * 256 + lane * 4);
;       v[0] *= rs * g[0]; v[1] *= rs * g[1]; v[2] *= rs * g[2]; v[3] *= rs * g[3]; *(f32x4*)(hr + i * 256 + lane * 4) = v; }
;   }
.LBB0_1912:
	s_or_b64 exec, exec, s[0:1]
	v_readlane_b32 s0, v240, 5
	v_readlane_b32 s1, v240, 6
	s_and_b64 vcc, exec, s[0:1]
	s_waitcnt lgkmcnt(0)
	s_barrier
	s_cbranch_vccnz .LBB0_1915
	s_load_dwordx4 s[4:7], s[38:39], 0x120
	s_load_dwordx2 s[2:3], s[38:39], 0x28
	v_lshlrev_b32_e32 v0, 4, v180
	v_ashrrev_i32_e32 v4, 6, v180
	v_and_b32_e32 v2, 0x3f0, v0
	s_waitcnt lgkmcnt(0)
	s_add_u32 s0, s6, 0x2bc8000
	v_mov_b32_e32 v3, 0
	s_addc_u32 s1, s7, 0
	v_lshl_add_u64 v[0:1], s[4:5], 0, v[2:3]
	v_lshl_add_u64 v[2:3], s[2:3], 0, v[2:3]
	v_add_u32_e32 v4, s37, v4
	s_lshl_b32 s2, s28, 3
	v_mov_b32_e32 v6, 0x358637bd
	s_mov_b32 s3, 0x800000
	global_load_dwordx4 v[24:27], v[2:3], off
	global_load_dwordx4 v[28:31], v[2:3], off offset:1024
	global_load_dwordx4 v[32:35], v[2:3], off offset:2048
	global_load_dwordx4 v[36:39], v[2:3], off offset:3072
	v_ashrrev_i32_e32 v5, 31, v4
	v_lshl_add_u64 v[60:61], v[4:5], 2, s[0:1]
	global_load_dword v7, v[60:61], off
	v_lshlrev_b64 v[60:61], 12, v[4:5]
	v_lshl_add_u64 v[62:63], v[0:1], 0, v[60:61]
	global_load_dwordx4 v[40:43], v[62:63], off
	global_load_dwordx4 v[44:47], v[62:63], off offset:1024
	global_load_dwordx4 v[48:51], v[62:63], off offset:2048
	global_load_dwordx4 v[52:55], v[62:63], off offset:3072
	s_waitcnt vmcnt(0)
	s_branch .Lfin_body
.Lfin_loop:
	s_waitcnt vmcnt(4)
.Lfin_body:
	v_mov_b64_e32 v[56:57], v[62:63]
	v_fmamk_f32 v5, v7, 0x3a800000, v6
	v_mul_f32_e32 v7, 0x4b800000, v5
	v_cmp_gt_f32_e32 vcc, s3, v5
	s_nop 1
	v_cndmask_b32_e32 v5, v5, v7, vcc
	v_rsq_f32_e32 v5, v5
	s_nop 0
	v_mul_f32_e32 v7, 0x45800000, v5
	v_cndmask_b32_e32 v58, v5, v7, vcc
	v_pk_mul_f32 v[8:9], v[24:25], v[58:59] op_sel_hi:[1,0]
	v_pk_mul_f32 v[10:11], v[26:27], v[58:59] op_sel_hi:[1,0]
	v_pk_mul_f32 v[8:9], v[40:41], v[8:9]
	v_pk_mul_f32 v[10:11], v[42:43], v[10:11]
	v_pk_mul_f32 v[12:13], v[28:29], v[58:59] op_sel_hi:[1,0]
	v_pk_mul_f32 v[14:15], v[30:31], v[58:59] op_sel_hi:[1,0]
	v_pk_mul_f32 v[12:13], v[44:45], v[12:13]
	v_pk_mul_f32 v[14:15], v[46:47], v[14:15]
	v_pk_mul_f32 v[16:17], v[32:33], v[58:59] op_sel_hi:[1,0]
	v_pk_mul_f32 v[18:19], v[34:35], v[58:59] op_sel_hi:[1,0]
	v_pk_mul_f32 v[16:17], v[48:49], v[16:17]
	v_pk_mul_f32 v[18:19], v[50:51], v[18:19]
	v_pk_mul_f32 v[20:21], v[36:37], v[58:59] op_sel_hi:[1,0]
	v_pk_mul_f32 v[22:23], v[38:39], v[58:59] op_sel_hi:[1,0]
	v_pk_mul_f32 v[20:21], v[52:53], v[20:21]
	v_pk_mul_f32 v[22:23], v[54:55], v[22:23]
	s_add_i32 s36, s36, s28
	s_cmpk_lt_i32 s36, 0x1800
	v_add_u32_e32 v4, s2, v4
	s_cbranch_scc0 .Lfin_last
	v_ashrrev_i32_e32 v5, 31, v4
	v_lshl_add_u64 v[60:61], v[4:5], 2, s[0:1]
	global_load_dword v7, v[60:61], off
	v_lshlrev_b64 v[60:61], 12, v[4:5]
	v_lshl_add_u64 v[62:63], v[0:1], 0, v[60:61]
	global_load_dwordx4 v[40:43], v[62:63], off
	global_load_dwordx4 v[44:47], v[62:63], off offset:1024
	global_load_dwordx4 v[48:51], v[62:63], off offset:2048
	global_load_dwordx4 v[52:55], v[62:63], off offset:3072
	global_store_dwordx4 v[56:57], v[8:11], off
	global_store_dwordx4 v[56:57], v[12:15], off offset:1024
	global_store_dwordx4 v[56:57], v[16:19], off offset:2048
	global_store_dwordx4 v[56:57], v[20:23], off offset:3072
	s_branch .Lfin_loop
.Lfin_last:
	global_store_dwordx4 v[56:57], v[8:11], off
	global_store_dwordx4 v[56:57], v[12:15], off offset:1024
	global_store_dwordx4 v[56:57], v[16:19], off offset:2048
	global_store_dwordx4 v[56:57], v[20:23], off offset:3072
